# diff attention: same peeled fast loop as MLA (below-diagonal tile pairs without activity logic, MFMA-first segment with stores/reads/next loads in MFMA shadows)
# baseline (speedup 1.0000x reference)
; #define ATT_BAR() do { asm volatile("s_waitcnt lgkmcnt(0)" ::: "memory"); __builtin_amdgcn_s_barrier(); asm volatile("" ::: "memory"); } while (0)
; template <int DK, int DV>
; __device__ __forceinline__ void attn_unit(LAS unsigned char* lds, const bf16* Qp, int ldq, const bf16* Kp, int ldk, const bf16* VTp, bf16* Op, int ldo, int qb) {
;     ...
;     ATT_LOAD(0, kra, vra); ATT_LOAD(1, krb, vrb);
;     ATT_STORE(0, kra, vra); ATT_STORE(BUF, krb, vrb);
;     ATT_LOAD(2, krb, vrb);
;     __syncthreads();
;     float mrun = 0.f, lrun = 0.f;
;     f32x16 o[NDB];
; #pragma unroll
;     for (int db = 0; db < NDB; ++db)
; #pragma unroll
;         for (int r = 0; r < 16; ++r) o[db][r] = 0.f;
;     f32x16 s0, s1;
;     const f32x16 zacc = {0.f, 0.f, 0.f, 0.f, 0.f, 0.f, 0.f, 0.f, 0.f, 0.f, 0.f, 0.f, 0.f, 0.f, 0.f, 0.f};
;     f32x16 negm = zacc;
;     constexpr float ATT_THR = 8.f;
;     ATT_QK(0, zacc);
;     if (grpB) ATT_BAR();
;     int bcur = 0, bnext = BUF, bfree = 2 * BUF;
; #pragma unroll 1
;     for (int t = 0; t < NT; t += 2) {
.LBB0_1071:
	ds_read_b128 v[232:235], v189
	ds_read_b128 v[236:239], v189 offset:1024
	ds_read_b128 v[240:243], v189 offset:2048
	ds_read_b128 v[244:247], v189 offset:3072
	v_mov_b32_e32 v14, v1
	v_mov_b32_e32 v15, v1
	s_lshl_b32 s43, s1, 2
	v_lshl_add_u64 v[182:183], v[2:3], 1, s[4:5]
	v_or_b32_e32 v192, s35, v4
	v_lshlrev_b32_e32 v191, 2, v5
	v_mov_b32_e32 v0, v1
	v_mov_b32_e32 v2, v1
	v_mov_b32_e32 v3, v1
	v_mov_b32_e32 v4, v1
	v_mov_b32_e32 v5, v1
	v_mov_b32_e32 v6, v1
	v_mov_b32_e32 v7, v1
	v_mov_b32_e32 v8, v1
	v_mov_b32_e32 v9, v1
	v_mov_b32_e32 v10, v1
	v_mov_b32_e32 v11, v1
	v_mov_b32_e32 v12, v1
	v_mov_b32_e32 v13, v1
	v_mov_b64_e32 v[30:31], v[14:15]
	v_mov_b64_e32 v[46:47], v[14:15]
	v_mov_b64_e32 v[62:63], v[14:15]
	v_mov_b64_e32 v[78:79], v[14:15]
	v_mov_b64_e32 v[126:127], v[14:15]
	s_lshl_b32 s42, s0, 13
	s_add_i32 s44, s43, 4
	s_or_b32 s45, s43, 3
	s_or_b32 s46, s35, 31
	s_mov_b32 s47, 0
	s_sub_i32 s48, 0, s43
	s_sub_i32 s49, 0, s8
	v_subrev_u32_e32 v194, s8, v191
	s_mov_b32 s50, 0xd800
	s_movk_i32 s51, 0x6c00
	v_mov_b32_e32 v193, 0
	v_mov_b64_e32 v[28:29], v[12:13]
	v_mov_b64_e32 v[26:27], v[10:11]
	v_mov_b64_e32 v[24:25], v[8:9]
	v_mov_b64_e32 v[22:23], v[6:7]
	v_mov_b64_e32 v[20:21], v[4:5]
	v_mov_b64_e32 v[18:19], v[2:3]
	v_mov_b64_e32 v[16:17], v[0:1]
	v_mov_b64_e32 v[44:45], v[12:13]
	v_mov_b64_e32 v[42:43], v[10:11]
	v_mov_b64_e32 v[40:41], v[8:9]
	v_mov_b64_e32 v[38:39], v[6:7]
	v_mov_b64_e32 v[36:37], v[4:5]
	v_mov_b64_e32 v[34:35], v[2:3]
	v_mov_b64_e32 v[32:33], v[0:1]
	v_mov_b64_e32 v[60:61], v[12:13]
	v_mov_b64_e32 v[58:59], v[10:11]
	v_mov_b64_e32 v[56:57], v[8:9]
	v_mov_b64_e32 v[54:55], v[6:7]
	v_mov_b64_e32 v[52:53], v[4:5]
	v_mov_b64_e32 v[50:51], v[2:3]
	v_mov_b64_e32 v[48:49], v[0:1]
	v_mov_b64_e32 v[76:77], v[12:13]
	v_mov_b64_e32 v[74:75], v[10:11]
	v_mov_b64_e32 v[72:73], v[8:9]
	v_mov_b64_e32 v[70:71], v[6:7]
	v_mov_b64_e32 v[68:69], v[4:5]
	v_mov_b64_e32 v[66:67], v[2:3]
	v_mov_b64_e32 v[64:65], v[0:1]
	v_mov_b32_e32 v195, 0
	v_mov_b64_e32 v[124:125], v[12:13]
	v_mov_b64_e32 v[122:123], v[10:11]
	v_mov_b64_e32 v[120:121], v[8:9]
	v_mov_b64_e32 v[118:119], v[6:7]
	v_mov_b64_e32 v[116:117], v[4:5]
	v_mov_b64_e32 v[114:115], v[2:3]
	v_mov_b64_e32 v[112:113], v[0:1]
	s_mov_b32 s0, 0
	s_mov_b32 s54, 0
	s_add_i32 s1, s54, 3
	s_cmp_lt_u32 s1, s44
	s_cselect_b32 s1, s1, s45
	s_lshl_b32 s8, s1, 6
	v_add_u32_e32 v2, s8, v174
	v_ashrrev_i32_e32 v3, 31, v2
	v_lshlrev_b64 v[2:3], 10, v[2:3]
	v_lshl_add_u64 v[6:7], s[8:9], 1, v[176:177]
	v_lshl_add_u64 v[2:3], v[182:183], 0, v[2:3]
	v_lshl_add_u64 v[4:5], v[6:7], 0, v[178:179]
	v_lshl_add_u64 v[6:7], v[6:7], 0, v[180:181]
	global_load_dwordx4 v[10:13], v[2:3], off
	s_nop 0
	global_load_dwordx4 v[2:5], v[4:5], off
	global_load_dwordx4 v[6:9], v[6:7], off
	s_add_i32 s4, s48, s54
	s_cmp_lt_i32 s4, -2
	s_cbranch_scc1 .Lfd_entry

.Lfd_entry:
	s_mov_b32 s55, s51
	s_mov_b32 s51, s0
.Lfd_head:
	v_add_u32_e32 v248, s51, v190
	ds_read_b128 v[196:199], v248 offset:9216
	ds_read_b128 v[200:203], v248 offset:13824
	ds_read_b128 v[204:207], v248 offset:18432
	ds_read_b128 v[208:211], v248 offset:23040
	ds_read_b128 v[212:215], v248 offset:9248
	ds_read_b128 v[216:219], v248 offset:13856
	ds_read_b128 v[220:223], v248 offset:18464
	ds_read_b128 v[224:227], v248 offset:23072
	v_max3_f32 v0, v80, v81, v82
	v_max3_f32 v14, v96, v97, v98
	v_max3_f32 v0, v0, v83, v84
	v_max3_f32 v14, v14, v99, v100
	v_max3_f32 v0, v0, v85, v86
	v_max3_f32 v14, v14, v101, v102
	v_max3_f32 v0, v0, v87, v88
	v_max3_f32 v14, v14, v103, v104
	v_max3_f32 v0, v0, v89, v90
	v_max3_f32 v14, v14, v105, v106
	v_max3_f32 v0, v0, v91, v92
	v_max3_f32 v14, v14, v107, v108
	v_max_f32_e32 v15, v111, v111
	v_max_f32_e32 v156, v95, v95
	v_max3_f32 v0, v0, v93, v94
	v_max3_f32 v14, v14, v109, v110
	v_max_f32_e32 v15, v156, v15
	v_max3_f32 v0, v0, v14, v15
	s_cmp_lg_u32 s47, 0
	s_cselect_b64 s[18:19], -1, 0
	s_cmp_eq_u32 s47, 0
	s_cbranch_scc1 .Lfd_a_xchg
	v_cmp_lt_f32_e32 vcc, s33, v0
	s_cbranch_vccnz .Lfd_a_xchg
.Lfd_a_exp:
	v_exp_f32_e32 v80, v80
	v_exp_f32_e32 v96, v96
	v_exp_f32_e32 v81, v81
	v_exp_f32_e32 v97, v97
	v_exp_f32_e32 v88, v88
	v_exp_f32_e32 v104, v104
	v_exp_f32_e32 v89, v89
	v_exp_f32_e32 v105, v105
	v_exp_f32_e32 v82, v82
	v_exp_f32_e32 v98, v98
	v_exp_f32_e32 v83, v83
	v_exp_f32_e32 v99, v99
	v_exp_f32_e32 v90, v90
	v_exp_f32_e32 v106, v106
	v_exp_f32_e32 v91, v91
	v_exp_f32_e32 v107, v107
	v_exp_f32_e32 v84, v84
	v_exp_f32_e32 v100, v100
	v_exp_f32_e32 v85, v85
	v_exp_f32_e32 v101, v101
	v_exp_f32_e32 v92, v92
	v_exp_f32_e32 v108, v108
	v_exp_f32_e32 v93, v93
	v_exp_f32_e32 v109, v109
	v_exp_f32_e32 v86, v86
	v_exp_f32_e32 v102, v102
	v_exp_f32_e32 v87, v87
	v_exp_f32_e32 v103, v103
	v_exp_f32_e32 v94, v94
	v_exp_f32_e32 v110, v110
	v_exp_f32_e32 v95, v95
	v_exp_f32_e32 v111, v111
	v_pk_add_f32 v[156:157], v[80:81], v[96:97]
	v_pk_add_f32 v[158:159], v[82:83], v[98:99]
	v_pk_add_f32 v[160:161], v[84:85], v[100:101]
	v_pk_add_f32 v[162:163], v[86:87], v[102:103]
	v_pk_add_f32 v[164:165], v[88:89], v[104:105]
	v_pk_add_f32 v[166:167], v[90:91], v[106:107]
	v_pk_add_f32 v[168:169], v[92:93], v[108:109]
	v_pk_add_f32 v[170:171], v[94:95], v[110:111]
	v_pk_add_f32 v[156:157], v[156:157], v[158:159]
	v_pk_add_f32 v[160:161], v[160:161], v[162:163]
	v_pk_add_f32 v[164:165], v[164:165], v[166:167]
	v_pk_add_f32 v[168:169], v[168:169], v[170:171]
	v_pk_add_f32 v[156:157], v[156:157], v[160:161]
	v_pk_add_f32 v[164:165], v[164:165], v[168:169]
	v_pk_add_f32 v[156:157], v[156:157], v[164:165]
	v_add_f32_e32 v0, v156, v157
	v_cvt_pk_bf16_f32 v156, v80, v81
	v_cvt_pk_bf16_f32 v157, v82, v83
	v_cvt_pk_bf16_f32 v158, v84, v85
	v_cvt_pk_bf16_f32 v159, v86, v87
	v_cvt_pk_bf16_f32 v160, v88, v89
	v_cvt_pk_bf16_f32 v161, v90, v91
	v_cvt_pk_bf16_f32 v162, v92, v93
	v_cvt_pk_bf16_f32 v163, v94, v95
	v_cvt_pk_bf16_f32 v164, v96, v97
	v_cvt_pk_bf16_f32 v165, v98, v99
	v_cvt_pk_bf16_f32 v166, v100, v101
	v_cvt_pk_bf16_f32 v167, v102, v103
	v_cvt_pk_bf16_f32 v168, v104, v105
	v_cvt_pk_bf16_f32 v169, v106, v107
	v_cvt_pk_bf16_f32 v170, v108, v109
	v_cvt_pk_bf16_f32 v171, v110, v111
	v_add_f32_e32 v193, v193, v0
	s_waitcnt lgkmcnt(0)
	s_barrier
	v_mfma_f32_32x32x16_bf16 v[64:79], v[196:199], v[156:159], v[64:79]
	s_setprio 1
	v_add_u32_e32 v14, s50, v188
	s_waitcnt vmcnt(3)
	ds_write_b128 v14, v[136:139]
	v_mfma_f32_32x32x16_bf16 v[48:63], v[200:203], v[156:159], v[48:63]
	ds_read_b128 v[196:199], v248 offset:9280
	v_add_u32_e32 v14, s50, v186
	v_add_u32_e32 v15, v14, v175
	v_mfma_f32_32x32x16_bf16 v[32:47], v[204:207], v[156:159], v[32:47]
	ds_read_b128 v[200:203], v248 offset:13888
	v_add_u32_e32 v14, v14, v187
	ds_write_b128 v15, v[128:131] offset:9216
	v_mfma_f32_32x32x16_bf16 v[16:31], v[208:211], v[156:159], v[16:31]
	ds_read_b128 v[204:207], v248 offset:18496
	ds_write_b128 v14, v[132:135] offset:9216
	v_mfma_f32_32x32x16_bf16 v[64:79], v[212:215], v[160:163], v[64:79]
	ds_read_b128 v[208:211], v248 offset:23104
	v_add_u32_e32 v249, s55, v190
	v_mfma_f32_32x32x16_bf16 v[48:63], v[216:219], v[160:163], v[48:63]
	ds_read_b128 v[212:215], v248 offset:9312
	v_mfma_f32_32x32x16_bf16 v[32:47], v[220:223], v[160:163], v[32:47]
	ds_read_b128 v[216:219], v248 offset:13920
	v_mfma_f32_32x32x16_bf16 v[16:31], v[224:227], v[160:163], v[16:31]
	ds_read_b128 v[220:223], v248 offset:18528
	ds_read_b128 v[224:227], v248 offset:23136
	s_waitcnt lgkmcnt(4)
	v_mfma_f32_32x32x16_bf16 v[64:79], v[196:199], v[164:167], v[64:79]
	ds_read_b128 v[196:199], v249
	s_add_i32 s0, s54, 4
	s_cmp_lt_u32 s54, s43
	v_mfma_f32_32x32x16_bf16 v[48:63], v[200:203], v[164:167], v[48:63]
	ds_read_b128 v[200:203], v249 offset:4608
	s_cselect_b32 s0, s0, s45
	s_lshl_b32 s8, s0, 6
	v_mfma_f32_32x32x16_bf16 v[32:47], v[204:207], v[164:167], v[32:47]
	ds_read_b128 v[204:207], v249 offset:32
	v_add_u32_e32 v14, s8, v174
	v_ashrrev_i32_e32 v15, 31, v14
	v_mfma_f32_32x32x16_bf16 v[16:31], v[208:211], v[164:167], v[16:31]
	ds_read_b128 v[208:211], v249 offset:4640
	v_lshlrev_b64 v[14:15], 10, v[14:15]
	v_lshl_add_u64 v[132:133], s[8:9], 1, v[176:177]
	s_waitcnt lgkmcnt(4)
	v_mfma_f32_32x32x16_bf16 v[64:79], v[212:215], v[168:171], v[64:79]
	ds_read_b128 v[212:215], v249 offset:64
	v_lshl_add_u64 v[14:15], v[182:183], 0, v[14:15]
	v_lshl_add_u64 v[128:129], v[132:133], 0, v[178:179]
	v_mfma_f32_32x32x16_bf16 v[48:63], v[216:219], v[168:171], v[48:63]
	ds_read_b128 v[216:219], v249 offset:4672
	global_load_dwordx4 v[136:139], v[14:15], off
	s_nop 0
	v_mfma_f32_32x32x16_bf16 v[32:47], v[220:223], v[168:171], v[32:47]
	ds_read_b128 v[220:223], v249 offset:96
	global_load_dwordx4 v[128:131], v[128:129], off
	v_lshl_add_u64 v[14:15], v[132:133], 0, v[180:181]
	v_mfma_f32_32x32x16_bf16 v[16:31], v[224:227], v[168:171], v[16:31]
	ds_read_b128 v[224:227], v249 offset:4704
	global_load_dwordx4 v[132:135], v[14:15], off
	s_waitcnt lgkmcnt(4)
	v_mfma_f32_32x32x16_bf16 v[80:95], v[196:199], v[232:235], v[112:127]
	v_mfma_f32_32x32x16_bf16 v[96:111], v[200:203], v[232:235], v[112:127]
	v_mfma_f32_32x32x16_bf16 v[80:95], v[204:207], v[236:239], v[80:95]
	v_mfma_f32_32x32x16_bf16 v[96:111], v[208:211], v[236:239], v[96:111]
	s_waitcnt lgkmcnt(0)
	v_mfma_f32_32x32x16_bf16 v[80:95], v[212:215], v[240:243], v[80:95]
	v_mfma_f32_32x32x16_bf16 v[96:111], v[216:219], v[240:243], v[96:111]
	v_mfma_f32_32x32x16_bf16 v[80:95], v[220:223], v[244:247], v[80:95]
	v_mfma_f32_32x32x16_bf16 v[96:111], v[224:227], v[244:247], v[96:111]
	s_setprio 0
	s_waitcnt lgkmcnt(0)
	s_barrier
; template <int DK, int DV>
; __device__ __forceinline__ void attn_unit(LAS unsigned char* lds, const bf16* Qp, int ldq, const bf16* Kp, int ldk, const bf16* VTp, bf16* Op, int ldo, int qb) {
;     ...
;     for (int t = 0; t < NT; t += 2) {
;         ATT_STEP(t, kra, vra, krb, vrb);
;         ATT_STEP(t + 1, krb, vrb, kra, vra);
;     }
	v_add_u32_e32 v248, s55, v190
	ds_read_b128 v[196:199], v248 offset:9216
	ds_read_b128 v[200:203], v248 offset:13824
	ds_read_b128 v[204:207], v248 offset:18432
	ds_read_b128 v[208:211], v248 offset:23040
	ds_read_b128 v[212:215], v248 offset:9248
	ds_read_b128 v[216:219], v248 offset:13856
	ds_read_b128 v[220:223], v248 offset:18464
	ds_read_b128 v[224:227], v248 offset:23072
	v_max3_f32 v14, v80, v81, v82
	v_max3_f32 v15, v96, v97, v98
	v_max3_f32 v14, v14, v83, v84
	v_max3_f32 v15, v15, v99, v100
	v_max3_f32 v14, v14, v85, v86
	v_max3_f32 v15, v15, v101, v102
	v_max3_f32 v14, v14, v87, v88
	v_max3_f32 v15, v15, v103, v104
	v_max3_f32 v14, v14, v89, v90
	v_max3_f32 v15, v15, v105, v106
	v_max3_f32 v14, v14, v91, v92
	v_max3_f32 v15, v15, v107, v108
	v_max_f32_e32 v140, v111, v111
	v_max_f32_e32 v141, v95, v95
	v_max3_f32 v14, v14, v93, v94
	v_max3_f32 v15, v15, v109, v110
	v_max_f32_e32 v140, v141, v140
	v_max3_f32 v14, v14, v15, v140
	v_cmp_lt_f32_e32 vcc, s33, v14
	s_cbranch_vccnz .Lfd_b_resc
.Lfd_b_exp:
	v_exp_f32_e32 v80, v80
	v_exp_f32_e32 v96, v96
	v_exp_f32_e32 v81, v81
	v_exp_f32_e32 v97, v97
	v_exp_f32_e32 v88, v88
	v_exp_f32_e32 v104, v104
	v_exp_f32_e32 v89, v89
	v_exp_f32_e32 v105, v105
	v_exp_f32_e32 v82, v82
	v_exp_f32_e32 v98, v98
	v_exp_f32_e32 v83, v83
	v_exp_f32_e32 v99, v99
	v_exp_f32_e32 v90, v90
	v_exp_f32_e32 v106, v106
	v_exp_f32_e32 v91, v91
	v_exp_f32_e32 v107, v107
	v_exp_f32_e32 v84, v84
	v_exp_f32_e32 v100, v100
	v_exp_f32_e32 v85, v85
	v_exp_f32_e32 v101, v101
	v_exp_f32_e32 v92, v92
	v_exp_f32_e32 v108, v108
	v_exp_f32_e32 v93, v93
	v_exp_f32_e32 v109, v109
	v_exp_f32_e32 v86, v86
	v_exp_f32_e32 v102, v102
	v_exp_f32_e32 v87, v87
	v_exp_f32_e32 v103, v103
	v_exp_f32_e32 v94, v94
	v_exp_f32_e32 v110, v110
	v_exp_f32_e32 v95, v95
	v_exp_f32_e32 v111, v111
	v_pk_add_f32 v[140:141], v[80:81], v[96:97]
	v_pk_add_f32 v[142:143], v[82:83], v[98:99]
	v_pk_add_f32 v[144:145], v[84:85], v[100:101]
	v_pk_add_f32 v[146:147], v[86:87], v[102:103]
	v_pk_add_f32 v[148:149], v[88:89], v[104:105]
	v_pk_add_f32 v[150:151], v[90:91], v[106:107]
	v_pk_add_f32 v[152:153], v[92:93], v[108:109]
	v_pk_add_f32 v[154:155], v[94:95], v[110:111]
	v_pk_add_f32 v[140:141], v[140:141], v[142:143]
	v_pk_add_f32 v[144:145], v[144:145], v[146:147]
	v_pk_add_f32 v[148:149], v[148:149], v[150:151]
	v_pk_add_f32 v[152:153], v[152:153], v[154:155]
	v_pk_add_f32 v[140:141], v[140:141], v[144:145]
	v_pk_add_f32 v[148:149], v[148:149], v[152:153]
	v_pk_add_f32 v[140:141], v[140:141], v[148:149]
	v_add_f32_e32 v14, v140, v141
	v_cvt_pk_bf16_f32 v140, v80, v81
	v_cvt_pk_bf16_f32 v141, v82, v83
	v_cvt_pk_bf16_f32 v142, v84, v85
	v_cvt_pk_bf16_f32 v143, v86, v87
	v_cvt_pk_bf16_f32 v144, v88, v89
	v_cvt_pk_bf16_f32 v145, v90, v91
	v_cvt_pk_bf16_f32 v146, v92, v93
	v_cvt_pk_bf16_f32 v147, v94, v95
	v_cvt_pk_bf16_f32 v148, v96, v97
	v_cvt_pk_bf16_f32 v149, v98, v99
	v_cvt_pk_bf16_f32 v150, v100, v101
	v_cvt_pk_bf16_f32 v151, v102, v103
	v_cvt_pk_bf16_f32 v152, v104, v105
	v_cvt_pk_bf16_f32 v153, v106, v107
	v_cvt_pk_bf16_f32 v154, v108, v109
	v_cvt_pk_bf16_f32 v155, v110, v111
	v_add_f32_e32 v193, v193, v14
	s_waitcnt lgkmcnt(0)
	s_barrier
	v_mfma_f32_32x32x16_bf16 v[64:79], v[196:199], v[140:143], v[64:79]
	s_setprio 1
	v_add_u32_e32 v0, s51, v188
	s_waitcnt vmcnt(5)
	ds_write_b128 v0, v[10:13]
	v_mfma_f32_32x32x16_bf16 v[48:63], v[200:203], v[140:143], v[48:63]
	ds_read_b128 v[196:199], v248 offset:9280
	v_add_u32_e32 v0, s51, v186
	v_add_u32_e32 v10, v0, v175
	v_mfma_f32_32x32x16_bf16 v[32:47], v[204:207], v[140:143], v[32:47]
	ds_read_b128 v[200:203], v248 offset:13888
	v_add_u32_e32 v0, v0, v187
	s_waitcnt vmcnt(4)
	ds_write_b128 v10, v[2:5] offset:9216
	v_mfma_f32_32x32x16_bf16 v[16:31], v[208:211], v[140:143], v[16:31]
	ds_read_b128 v[204:207], v248 offset:18496
	s_waitcnt vmcnt(3)
	ds_write_b128 v0, v[6:9] offset:9216
	v_mfma_f32_32x32x16_bf16 v[64:79], v[212:215], v[144:147], v[64:79]
	ds_read_b128 v[208:211], v248 offset:23104
	v_add_u32_e32 v249, s50, v190
	v_mfma_f32_32x32x16_bf16 v[48:63], v[216:219], v[144:147], v[48:63]
	ds_read_b128 v[212:215], v248 offset:9312
	s_add_i32 s54, s54, 2
	s_mov_b32 s0, s51
	v_mfma_f32_32x32x16_bf16 v[32:47], v[220:223], v[144:147], v[32:47]
	ds_read_b128 v[216:219], v248 offset:13920
	s_mov_b32 s51, s50
	s_mov_b32 s50, s55
	v_mfma_f32_32x32x16_bf16 v[16:31], v[224:227], v[144:147], v[16:31]
	ds_read_b128 v[220:223], v248 offset:18528
	ds_read_b128 v[224:227], v248 offset:23136
	s_mov_b32 s55, s0
	s_addk_i32 s47, 0x80
	s_waitcnt lgkmcnt(4)
	v_mfma_f32_32x32x16_bf16 v[64:79], v[196:199], v[148:151], v[64:79]
	ds_read_b128 v[196:199], v249
	s_add_i32 s1, s54, 3
	s_cmp_lt_u32 s1, s44
	v_mfma_f32_32x32x16_bf16 v[48:63], v[200:203], v[148:151], v[48:63]
	ds_read_b128 v[200:203], v249 offset:4608
	s_cselect_b32 s1, s1, s45
	s_lshl_b32 s8, s1, 6
	v_mfma_f32_32x32x16_bf16 v[32:47], v[204:207], v[148:151], v[32:47]
	ds_read_b128 v[204:207], v249 offset:32
	v_add_u32_e32 v2, s8, v174
	v_ashrrev_i32_e32 v3, 31, v2
	v_mfma_f32_32x32x16_bf16 v[16:31], v[208:211], v[148:151], v[16:31]
	ds_read_b128 v[208:211], v249 offset:4640
	v_lshlrev_b64 v[2:3], 10, v[2:3]
	v_lshl_add_u64 v[6:7], s[8:9], 1, v[176:177]
	s_waitcnt lgkmcnt(4)
	v_mfma_f32_32x32x16_bf16 v[64:79], v[212:215], v[152:155], v[64:79]
	ds_read_b128 v[212:215], v249 offset:64
	v_lshl_add_u64 v[2:3], v[182:183], 0, v[2:3]
	v_lshl_add_u64 v[4:5], v[6:7], 0, v[178:179]
	v_mfma_f32_32x32x16_bf16 v[48:63], v[216:219], v[152:155], v[48:63]
	ds_read_b128 v[216:219], v249 offset:4672
	v_lshl_add_u64 v[6:7], v[6:7], 0, v[180:181]
	global_load_dwordx4 v[10:13], v[2:3], off
	v_mfma_f32_32x32x16_bf16 v[32:47], v[220:223], v[152:155], v[32:47]
	ds_read_b128 v[220:223], v249 offset:96
	s_nop 0
	global_load_dwordx4 v[2:5], v[4:5], off
	v_mfma_f32_32x32x16_bf16 v[16:31], v[224:227], v[152:155], v[16:31]
	ds_read_b128 v[224:227], v249 offset:4704
	global_load_dwordx4 v[6:9], v[6:7], off
	s_waitcnt lgkmcnt(4)
	v_mfma_f32_32x32x16_bf16 v[80:95], v[196:199], v[232:235], v[112:127]
	v_mfma_f32_32x32x16_bf16 v[96:111], v[200:203], v[232:235], v[112:127]
	v_mfma_f32_32x32x16_bf16 v[80:95], v[204:207], v[236:239], v[80:95]
	v_mfma_f32_32x32x16_bf16 v[96:111], v[208:211], v[236:239], v[96:111]
	s_waitcnt lgkmcnt(0)
	v_mfma_f32_32x32x16_bf16 v[80:95], v[212:215], v[240:243], v[80:95]
	v_mfma_f32_32x32x16_bf16 v[96:111], v[216:219], v[240:243], v[96:111]
	s_add_i32 s4, s48, s54
	v_mfma_f32_32x32x16_bf16 v[80:95], v[220:223], v[244:247], v[80:95]
	v_mfma_f32_32x32x16_bf16 v[96:111], v[224:227], v[244:247], v[96:111]
	s_cmp_lt_i32 s4, -2
	s_setprio 0
	s_waitcnt lgkmcnt(0)
	s_barrier
	s_cbranch_scc1 .Lfd_head
	s_mov_b32 s0, s51
	s_mov_b32 s51, s55
	s_branch .LBB0_1072

.Lfd_a_1082:
	v_add_f32_e32 v195, v195, v0
	v_xor_b32_e32 v112, 0x80000000, v195
	v_sub_f32_e32 v95, v95, v0
	v_sub_f32_e32 v94, v94, v0
	v_sub_f32_e32 v93, v93, v0
	v_sub_f32_e32 v92, v92, v0
	v_sub_f32_e32 v91, v91, v0
	v_sub_f32_e32 v90, v90, v0
	v_sub_f32_e32 v89, v89, v0
	v_sub_f32_e32 v88, v88, v0
	v_sub_f32_e32 v87, v87, v0
	v_sub_f32_e32 v86, v86, v0
	v_sub_f32_e32 v85, v85, v0
	v_sub_f32_e32 v84, v84, v0
	v_sub_f32_e32 v83, v83, v0
	v_sub_f32_e32 v82, v82, v0
	v_sub_f32_e32 v81, v81, v0
	v_sub_f32_e32 v80, v80, v0
	v_sub_f32_e32 v111, v111, v0
	v_sub_f32_e32 v110, v110, v0
	v_sub_f32_e32 v109, v109, v0
	v_sub_f32_e32 v108, v108, v0
	v_sub_f32_e32 v107, v107, v0
	v_sub_f32_e32 v106, v106, v0
	v_sub_f32_e32 v105, v105, v0
	v_sub_f32_e32 v104, v104, v0
	v_sub_f32_e32 v103, v103, v0
	v_sub_f32_e32 v102, v102, v0
	v_sub_f32_e32 v101, v101, v0
	v_sub_f32_e32 v100, v100, v0
	v_sub_f32_e32 v99, v99, v0
	v_sub_f32_e32 v98, v98, v0
	v_sub_f32_e32 v97, v97, v0
	v_sub_f32_e32 v96, v96, v0
	v_mov_b32_e32 v113, v112
	v_mov_b32_e32 v114, v112
	v_mov_b32_e32 v115, v112
	v_mov_b32_e32 v116, v112
	v_mov_b32_e32 v117, v112
	v_mov_b32_e32 v118, v112
	v_mov_b32_e32 v119, v112
	v_mov_b32_e32 v120, v112
	v_mov_b32_e32 v121, v112
	v_mov_b32_e32 v122, v112
	v_mov_b32_e32 v123, v112
	v_mov_b32_e32 v124, v112
	v_mov_b32_e32 v125, v112
	v_mov_b32_e32 v126, v112
	v_mov_b32_e32 v127, v112
	s_branch .Lfd_a_exp
.Lfd_b_resc:
	ds_bpermute_b32 v15, v184, v14
	s_waitcnt lgkmcnt(0)
	v_max_f32_e32 v15, v15, v15
	v_max_f32_e32 v14, v14, v15
	v_max_f32_e32 v14, v14, v14
	v_max_f32_e32 v15, 0, v14
	v_exp_f32_e64 v14, -v15
	v_add_f32_e32 v195, v195, v15
	v_xor_b32_e32 v112, 0x80000000, v195
	v_sub_f32_e32 v95, v95, v15
	v_sub_f32_e32 v94, v94, v15
	v_sub_f32_e32 v93, v93, v15
	v_sub_f32_e32 v92, v92, v15
	v_sub_f32_e32 v91, v91, v15
	v_sub_f32_e32 v90, v90, v15
	v_sub_f32_e32 v89, v89, v15
	v_sub_f32_e32 v88, v88, v15
	v_sub_f32_e32 v87, v87, v15
	v_sub_f32_e32 v86, v86, v15
	v_sub_f32_e32 v85, v85, v15
	v_sub_f32_e32 v84, v84, v15
	v_sub_f32_e32 v83, v83, v15
	v_sub_f32_e32 v82, v82, v15
	v_sub_f32_e32 v81, v81, v15
	v_sub_f32_e32 v80, v80, v15
	v_pk_mul_f32 v[78:79], v[78:79], v[14:15] op_sel_hi:[1,0]
	v_pk_mul_f32 v[76:77], v[76:77], v[14:15] op_sel_hi:[1,0]
	v_pk_mul_f32 v[74:75], v[74:75], v[14:15] op_sel_hi:[1,0]
	v_pk_mul_f32 v[72:73], v[72:73], v[14:15] op_sel_hi:[1,0]
	v_pk_mul_f32 v[70:71], v[70:71], v[14:15] op_sel_hi:[1,0]
	v_pk_mul_f32 v[68:69], v[68:69], v[14:15] op_sel_hi:[1,0]
	v_pk_mul_f32 v[66:67], v[66:67], v[14:15] op_sel_hi:[1,0]
	v_pk_mul_f32 v[64:65], v[64:65], v[14:15] op_sel_hi:[1,0]
	v_pk_mul_f32 v[62:63], v[62:63], v[14:15] op_sel_hi:[1,0]
	v_pk_mul_f32 v[60:61], v[60:61], v[14:15] op_sel_hi:[1,0]
	v_pk_mul_f32 v[58:59], v[58:59], v[14:15] op_sel_hi:[1,0]
	v_pk_mul_f32 v[56:57], v[56:57], v[14:15] op_sel_hi:[1,0]
	v_pk_mul_f32 v[54:55], v[54:55], v[14:15] op_sel_hi:[1,0]
	v_pk_mul_f32 v[52:53], v[52:53], v[14:15] op_sel_hi:[1,0]
	v_pk_mul_f32 v[50:51], v[50:51], v[14:15] op_sel_hi:[1,0]
	v_pk_mul_f32 v[48:49], v[48:49], v[14:15] op_sel_hi:[1,0]
	v_pk_mul_f32 v[46:47], v[46:47], v[14:15] op_sel_hi:[1,0]
	v_pk_mul_f32 v[44:45], v[44:45], v[14:15] op_sel_hi:[1,0]
	v_pk_mul_f32 v[42:43], v[42:43], v[14:15] op_sel_hi:[1,0]
	v_pk_mul_f32 v[40:41], v[40:41], v[14:15] op_sel_hi:[1,0]
	v_pk_mul_f32 v[38:39], v[38:39], v[14:15] op_sel_hi:[1,0]
	v_pk_mul_f32 v[36:37], v[36:37], v[14:15] op_sel_hi:[1,0]
	v_pk_mul_f32 v[34:35], v[34:35], v[14:15] op_sel_hi:[1,0]
	v_pk_mul_f32 v[32:33], v[32:33], v[14:15] op_sel_hi:[1,0]
	v_pk_mul_f32 v[30:31], v[30:31], v[14:15] op_sel_hi:[1,0]
	v_pk_mul_f32 v[28:29], v[28:29], v[14:15] op_sel_hi:[1,0]
	v_pk_mul_f32 v[26:27], v[26:27], v[14:15] op_sel_hi:[1,0]
	v_pk_mul_f32 v[24:25], v[24:25], v[14:15] op_sel_hi:[1,0]
	v_pk_mul_f32 v[22:23], v[22:23], v[14:15] op_sel_hi:[1,0]
	v_pk_mul_f32 v[20:21], v[20:21], v[14:15] op_sel_hi:[1,0]
	v_pk_mul_f32 v[18:19], v[18:19], v[14:15] op_sel_hi:[1,0]
	v_pk_mul_f32 v[16:17], v[16:17], v[14:15] op_sel_hi:[1,0]
	v_sub_f32_e32 v111, v111, v15
	v_sub_f32_e32 v110, v110, v15
	v_sub_f32_e32 v109, v109, v15
	v_sub_f32_e32 v108, v108, v15
	v_sub_f32_e32 v107, v107, v15
	v_sub_f32_e32 v106, v106, v15
	v_sub_f32_e32 v105, v105, v15
	v_sub_f32_e32 v104, v104, v15
	v_sub_f32_e32 v103, v103, v15
	v_sub_f32_e32 v102, v102, v15
	v_sub_f32_e32 v101, v101, v15
	v_sub_f32_e32 v100, v100, v15
	v_sub_f32_e32 v99, v99, v15
	v_sub_f32_e32 v98, v98, v15
	v_sub_f32_e32 v97, v97, v15
	v_sub_f32_e32 v96, v96, v15
	v_mov_b32_e32 v113, v112
	v_mov_b32_e32 v114, v112
	v_mov_b32_e32 v115, v112
	v_mov_b32_e32 v116, v112
	v_mov_b32_e32 v117, v112
	v_mov_b32_e32 v118, v112
	v_mov_b32_e32 v119, v112
	v_mov_b32_e32 v120, v112
	v_mov_b32_e32 v121, v112
	v_mov_b32_e32 v122, v112
	v_mov_b32_e32 v123, v112
	v_mov_b32_e32 v124, v112
	v_mov_b32_e32 v125, v112
	v_mov_b32_e32 v126, v112
	v_mov_b32_e32 v127, v112
	v_mul_f32_e32 v193, v193, v14
	s_branch .Lfd_b_exp
